# gates GEMM epilogue: row sums and first y_a/y_b rows requested before the K loop, head vmcnt(0) removed
# baseline (speedup 1.0000x reference)
; template <class Epi, class Sched, bool ALIGN_EPI = false, bool SP2 = false>
; __device__ __forceinline__ void gemm_phase(LAS unsigned char* lds, const Gemm g, const Sched S, const Epi E) {
;     ...
; #pragma unroll
;         for (int a = 0; a < 2; ++a)
; #pragma unroll
;             for (int b = 0; b < 2; ++b)
; #pragma unroll
;                 for (int m = 0; m < 4; ++m)
; #pragma unroll
;                     for (int n = 0; n < 2; ++n) acc[a][b][m][n] = (f32x4){0.f, 0.f, 0.f, 0.f};
;         cur = nxt; cA = nA; cB = nB; ++ui;
.LBB0_1687:
	s_ashr_i32 s19, s18, 31
	s_lshl_b64 s[34:35], s[18:19], 20
	s_add_u32 s46, s24, s34
	s_addc_u32 s47, s25, s35
	s_and_b64 s[34:35], s[6:7], exec
	s_cselect_b32 s19, s47, s53
	s_cselect_b32 s62, s46, s52
	s_ashr_i32 s17, s16, 31
	s_lshl_b64 s[34:35], s[16:17], 19
	s_add_u32 s48, s42, s34
	s_addc_u32 s49, s43, s35
	s_and_b64 s[34:35], s[6:7], exec
	s_cselect_b32 s17, s49, s55
	s_cselect_b32 s63, s48, s54
	s_add_u32 s52, s52, 0x80080
	s_addc_u32 s53, s53, 0
	s_add_u32 s64, s54, 0x100
	v_mov_b32_e32 v0, 0
	s_addc_u32 s65, s55, 0
	s_mov_b32 s66, -2
	v_mov_b32_e32 v1, v0
	v_mov_b32_e32 v2, v0
	v_mov_b32_e32 v3, v0
	v_mov_b32_e32 v4, v0
	v_mov_b32_e32 v5, v0
	v_mov_b32_e32 v6, v0
	v_mov_b32_e32 v7, v0
	v_mov_b32_e32 v16, v0
	v_mov_b32_e32 v17, v0
	v_mov_b32_e32 v18, v0
	v_mov_b32_e32 v19, v0
	v_mov_b32_e32 v20, v0
	v_mov_b32_e32 v21, v0
	v_mov_b32_e32 v22, v0
	v_mov_b32_e32 v23, v0
	v_mov_b32_e32 v32, v0
	v_mov_b32_e32 v33, v0
	v_mov_b32_e32 v34, v0
	v_mov_b32_e32 v35, v0
	v_mov_b32_e32 v36, v0
	v_mov_b32_e32 v37, v0
	v_mov_b32_e32 v38, v0
	v_mov_b32_e32 v39, v0
	v_mov_b32_e32 v48, v0
	v_mov_b32_e32 v49, v0
	v_mov_b32_e32 v50, v0
	v_mov_b32_e32 v51, v0
	v_mov_b32_e32 v52, v0
	v_mov_b32_e32 v53, v0
	v_mov_b32_e32 v54, v0
	v_mov_b32_e32 v55, v0
	v_mov_b32_e32 v8, v0
	v_mov_b32_e32 v9, v0
	v_mov_b32_e32 v10, v0
	v_mov_b32_e32 v11, v0
	v_mov_b32_e32 v12, v0
	v_mov_b32_e32 v13, v0
	v_mov_b32_e32 v14, v0
	v_mov_b32_e32 v15, v0
	v_mov_b32_e32 v24, v0
	v_mov_b32_e32 v25, v0
	v_mov_b32_e32 v26, v0
	v_mov_b32_e32 v27, v0
	v_mov_b32_e32 v28, v0
	v_mov_b32_e32 v29, v0
	v_mov_b32_e32 v30, v0
	v_mov_b32_e32 v31, v0
	v_mov_b32_e32 v40, v0
	v_mov_b32_e32 v41, v0
	v_mov_b32_e32 v42, v0
	v_mov_b32_e32 v43, v0
	v_mov_b32_e32 v44, v0
	v_mov_b32_e32 v45, v0
	v_mov_b32_e32 v46, v0
	v_mov_b32_e32 v47, v0
	v_mov_b32_e32 v56, v0
	v_mov_b32_e32 v57, v0
	v_mov_b32_e32 v58, v0
	v_mov_b32_e32 v59, v0
	v_mov_b32_e32 v60, v0
	v_mov_b32_e32 v61, v0
	v_mov_b32_e32 v62, v0
	v_mov_b32_e32 v63, v0
	v_mov_b32_e32 v64, v0
	v_mov_b32_e32 v65, v0
	v_mov_b32_e32 v66, v0
	v_mov_b32_e32 v67, v0
	v_mov_b32_e32 v68, v0
	v_mov_b32_e32 v69, v0
	v_mov_b32_e32 v70, v0
	v_mov_b32_e32 v71, v0
	v_mov_b32_e32 v80, v0
	v_mov_b32_e32 v81, v0
	v_mov_b32_e32 v82, v0
	v_mov_b32_e32 v83, v0
	v_mov_b32_e32 v84, v0
	v_mov_b32_e32 v85, v0
	v_mov_b32_e32 v86, v0
	v_mov_b32_e32 v87, v0
	v_mov_b32_e32 v96, v0
	v_mov_b32_e32 v97, v0
	v_mov_b32_e32 v98, v0
	v_mov_b32_e32 v99, v0
	v_mov_b32_e32 v100, v0
	v_mov_b32_e32 v101, v0
	v_mov_b32_e32 v102, v0
	v_mov_b32_e32 v103, v0
	v_mov_b32_e32 v112, v0
	v_mov_b32_e32 v113, v0
	v_mov_b32_e32 v114, v0
	v_mov_b32_e32 v115, v0
	v_mov_b32_e32 v116, v0
	v_mov_b32_e32 v117, v0
	v_mov_b32_e32 v118, v0
	v_mov_b32_e32 v119, v0
	v_mov_b32_e32 v72, v0
	v_mov_b32_e32 v73, v0
	v_mov_b32_e32 v74, v0
	v_mov_b32_e32 v75, v0
	v_mov_b32_e32 v76, v0
	v_mov_b32_e32 v77, v0
	v_mov_b32_e32 v78, v0
	v_mov_b32_e32 v79, v0
	v_mov_b32_e32 v88, v0
	v_mov_b32_e32 v89, v0
	v_mov_b32_e32 v90, v0
	v_mov_b32_e32 v91, v0
	v_mov_b32_e32 v92, v0
	v_mov_b32_e32 v93, v0
	v_mov_b32_e32 v94, v0
	v_mov_b32_e32 v95, v0
	v_mov_b32_e32 v104, v0
	v_mov_b32_e32 v105, v0
	v_mov_b32_e32 v106, v0
	v_mov_b32_e32 v107, v0
	v_mov_b32_e32 v108, v0
	v_mov_b32_e32 v109, v0
	v_mov_b32_e32 v110, v0
	v_mov_b32_e32 v111, v0
	v_mov_b32_e32 v120, v0
	v_mov_b32_e32 v121, v0
	v_mov_b32_e32 v122, v0
	v_mov_b32_e32 v123, v0
	v_mov_b32_e32 v124, v0
	v_mov_b32_e32 v125, v0
	v_mov_b32_e32 v126, v0
	v_mov_b32_e32 v127, v0
	v_lshl_add_u32 v252, s8, 8, v164
	v_ashrrev_i32_e32 v253, 31, v252
	v_lshl_add_u64 v[254:255], v[252:253], 2, s[26:27]
	global_load_dword v244, v[254:255], off
	global_load_dword v245, v[254:255], off offset:64
	global_load_dword v246, v[254:255], off offset:128
	global_load_dword v247, v[254:255], off offset:192
	global_load_dword v248, v[254:255], off offset:512
	global_load_dword v249, v[254:255], off offset:576
	global_load_dword v250, v[254:255], off offset:640
	global_load_dword v251, v[254:255], off offset:704
	v_lshl_or_b32 v240, s9, 7, v166
	v_ashrrev_i32_e32 v241, 31, v240
	v_lshlrev_b64 v[240:241], 1, v[240:241]
	v_lshl_add_u64 v[228:229], s[50:51], 0, v[240:241]
	v_lshl_add_u64 v[240:241], s[40:41], 0, v[240:241]
	v_lshlrev_b64 v[254:255], 11, v[252:253]
	v_lshl_add_u64 v[254:255], v[228:229], 0, v[254:255]
	global_load_dwordx4 v[224:227], v[254:255], off
	v_mad_i64_i32 v[254:255], s[100:101], v252, s61, v[240:241]
	global_load_dwordx4 v[232:235], v[254:255], off
	v_or_b32_e32 v252, 16, v252
	v_ashrrev_i32_e32 v253, 31, v252
	v_lshlrev_b64 v[254:255], 11, v[252:253]
	v_lshl_add_u64 v[254:255], v[228:229], 0, v[254:255]
	global_load_dwordx4 v[236:239], v[254:255], off
	v_mad_i64_i32 v[254:255], s[100:101], v252, s61, v[240:241]
	s_nop 0
	global_load_dwordx4 v[252:255], v[254:255], off

.LBB0_1691:
	v_lshl_add_u32 v154, s8, 8, v164
	v_ashrrev_i32_e32 v155, 31, v154
	v_lshl_add_u64 v[128:129], v[154:155], 2, s[26:27]
	v_mov_b32_e32 v175, v244
	v_mov_b32_e32 v186, v245
	v_mov_b32_e32 v191, v246
	v_mov_b32_e32 v193, v247
	v_mov_b32_e32 v173, v248
	v_mov_b32_e32 v174, v249
	v_mov_b32_e32 v171, v250
	v_mov_b32_e32 v172, v251
	v_lshl_or_b32 v128, s9, 7, v166
	v_ashrrev_i32_e32 v129, 31, v128
	v_lshlrev_b64 v[152:153], 1, v[128:129]
	v_lshl_add_u64 v[158:159], s[50:51], 0, v[152:153]
	v_lshlrev_b64 v[184:185], 11, v[154:155]
	v_lshl_add_u64 v[156:157], s[40:41], 0, v[152:153]
	v_lshl_add_u64 v[128:129], v[158:159], 0, v[184:185]
	v_mov_b64_e32 v[176:177], v[224:225]
	v_mov_b64_e32 v[178:179], v[226:227]
	v_mad_i64_i32 v[128:129], s[8:9], v154, s61, v[156:157]
	v_mov_b64_e32 v[180:181], v[232:233]
	v_mov_b64_e32 v[182:183], v[234:235]
	v_or_b32_e32 v128, 16, v154
	v_ashrrev_i32_e32 v129, 31, v128
	v_lshlrev_b64 v[162:163], 11, v[128:129]
	v_lshl_add_u64 v[130:131], v[158:159], 0, v[162:163]
	v_mad_i64_i32 v[128:129], s[8:9], v128, s61, v[156:157]
	v_mov_b64_e32 v[132:133], v[236:237]
	v_mov_b64_e32 v[134:135], v[238:239]
	s_nop 0
	v_mov_b64_e32 v[128:129], v[252:253]
	v_mov_b64_e32 v[130:131], v[254:255]
	v_or_b32_e32 v160, 32, v154
	v_ashrrev_i32_e32 v161, 31, v160
	v_fmamk_f32 v155, v175, 0x3a800000, v170
	v_fmamk_f32 v175, v186, 0x3a800000, v170
	v_mul_f32_e32 v186, 0x4b800000, v155
	v_cmp_gt_f32_e32 vcc, s60, v155
	v_mul_f32_e32 v187, 0x4b800000, v175
	v_cmp_gt_f32_e64 s[8:9], s60, v175
	v_cndmask_b32_e32 v155, v155, v186, vcc
	v_rsq_f32_e32 v155, v155
	v_cndmask_b32_e64 v175, v175, v187, s[8:9]
	v_rsq_f32_e32 v175, v175
	v_mul_f32_e32 v190, 0x45800000, v155
	v_cndmask_b32_e32 v190, v155, v190, vcc
	v_pk_mul_f32 v[126:127], v[126:127], v[190:191] op_sel_hi:[1,0]
	v_pk_mul_f32 v[124:125], v[124:125], v[190:191] op_sel_hi:[1,0]
	v_pk_mul_f32 v[118:119], v[118:119], v[190:191] op_sel_hi:[1,0]
	v_pk_mul_f32 v[116:117], v[116:117], v[190:191] op_sel_hi:[1,0]
	v_mul_f32_e32 v124, 0xbfb8aa3b, v124
	v_mul_f32_e32 v116, 0xbfb8aa3b, v116
	v_mul_f32_e32 v117, 0xbfb8aa3b, v117
	v_mul_f32_e32 v126, 0xbfb8aa3b, v126
	v_mul_f32_e32 v118, 0xbfb8aa3b, v118
	v_mul_f32_e32 v127, 0xbfb8aa3b, v127
	v_mul_f32_e32 v119, 0xbfb8aa3b, v119
	v_mul_f32_e32 v125, 0xbfb8aa3b, v125
	v_exp_f32_e32 v124, v124
	v_exp_f32_e32 v116, v116
	v_exp_f32_e32 v117, v117
	v_exp_f32_e32 v126, v126
	v_exp_f32_e32 v118, v118
	v_exp_f32_e32 v127, v127
	v_exp_f32_e32 v119, v119
	v_exp_f32_e32 v125, v125
	v_pk_mul_f32 v[112:113], v[112:113], v[190:191] op_sel_hi:[1,0]
	v_mul_f32_e32 v192, 0x45800000, v175
	v_mul_f32_e32 v112, 0xbfb8aa3b, v112
	v_cndmask_b32_e64 v192, v175, v192, s[8:9]
	v_pk_mul_f32 v[122:123], v[122:123], v[190:191] op_sel_hi:[1,0]
	v_pk_mul_f32 v[120:121], v[120:121], v[190:191] op_sel_hi:[1,0]
	v_pk_mul_f32 v[114:115], v[114:115], v[190:191] op_sel_hi:[1,0]
	v_exp_f32_e32 v155, v112
	v_add_f32_e32 v112, 1.0, v124
	v_add_f32_e32 v124, 1.0, v116
	v_add_f32_e32 v175, 1.0, v117
	v_add_f32_e32 v126, 1.0, v126
	v_add_f32_e32 v190, 1.0, v118
	v_add_f32_e32 v194, 1.0, v127
	v_add_f32_e32 v127, 1.0, v119
	v_add_f32_e32 v125, 1.0, v125
	v_rcp_f32_e32 v118, v124
	v_rcp_f32_e32 v119, v175
	v_rcp_f32_e32 v124, v126
	v_rcp_f32_e32 v126, v190
	v_rcp_f32_e32 v127, v127
	v_rcp_f32_e32 v116, v112
	v_rcp_f32_e32 v117, v125
	v_rcp_f32_e32 v125, v194
	v_lshlrev_b32_e32 v188, 16, v180
	v_and_b32_e32 v189, 0xffff0000, v180
	v_lshlrev_b32_e32 v180, 16, v181
	v_and_b32_e32 v181, 0xffff0000, v181
	v_mul_f32_e32 v120, 0xbfb8aa3b, v120
	v_lshlrev_b32_e32 v186, 16, v176
	v_and_b32_e32 v187, 0xffff0000, v176
	v_lshlrev_b32_e32 v176, 16, v177
	v_and_b32_e32 v177, 0xffff0000, v177
	v_exp_f32_e32 v120, v120
	v_pk_mul_f32 v[118:119], v[118:119], v[188:189]
	v_pk_mul_f32 v[126:127], v[126:127], v[180:181]
	v_mul_f32_e32 v121, 0xbfb8aa3b, v121
	v_mul_f32_e32 v113, 0xbfb8aa3b, v113
	v_pk_fma_f32 v[116:117], v[116:117], v[186:187], v[118:119]
	v_pk_fma_f32 v[118:119], v[124:125], v[176:177], v[126:127]
	v_exp_f32_e32 v121, v121
	v_exp_f32_e32 v124, v113
	v_add_f32_e32 v120, 1.0, v120
	v_rcp_f32_e32 v112, v120
	v_add_f32_e32 v120, 1.0, v155
	v_add_f32_e32 v113, 1.0, v121
	v_add_f32_e32 v121, 1.0, v124
	v_rcp_f32_e32 v120, v120
	v_rcp_f32_e32 v121, v121
	v_mul_f32_e32 v114, 0xbfb8aa3b, v114
	v_rcp_f32_e32 v113, v113
	v_mul_f32_e32 v122, 0xbfb8aa3b, v122
	v_exp_f32_e32 v114, v114
	v_exp_f32_e32 v122, v122
	v_lshlrev_b32_e32 v126, 16, v182
	v_and_b32_e32 v127, 0xffff0000, v182
	v_lshlrev_b32_e32 v124, 16, v178
	v_and_b32_e32 v125, 0xffff0000, v178
	v_pk_mul_f32 v[120:121], v[120:121], v[126:127]
	v_pk_mul_f32 v[108:109], v[108:109], v[192:193] op_sel_hi:[1,0]
	v_pk_fma_f32 v[120:121], v[112:113], v[124:125], v[120:121]
	v_add_f32_e32 v113, 1.0, v114
	v_mul_f32_e32 v114, 0xbfb8aa3b, v123
	v_add_f32_e32 v112, 1.0, v122
	v_exp_f32_e32 v122, v114
	v_mul_f32_e32 v114, 0xbfb8aa3b, v115
	v_exp_f32_e32 v115, v114
	v_rcp_f32_e32 v114, v113
	v_add_f32_e32 v113, 1.0, v122
	v_rcp_f32_e32 v112, v112
	v_add_f32_e32 v115, 1.0, v115
	v_rcp_f32_e32 v115, v115
	v_rcp_f32_e32 v113, v113
	v_lshlrev_b32_e32 v124, 16, v183
	v_and_b32_e32 v125, 0xffff0000, v183
	v_lshlrev_b32_e32 v122, 16, v179
	v_and_b32_e32 v123, 0xffff0000, v179
	v_pk_mul_f32 v[114:115], v[114:115], v[124:125]
	v_pk_mul_f32 v[100:101], v[100:101], v[192:193] op_sel_hi:[1,0]
	v_pk_fma_f32 v[122:123], v[112:113], v[122:123], v[114:115]
	v_cvt_pk_bf16_f32 v112, v116, v117
	v_lshl_add_u64 v[116:117], s[50:51], 0, v[184:185]
	v_cvt_pk_bf16_f32 v113, v118, v119
	v_cvt_pk_bf16_f32 v114, v120, v121
	v_cvt_pk_bf16_f32 v115, v122, v123
	v_lshl_add_u64 v[116:117], v[116:117], 0, v[152:153]
	v_mul_f32_e32 v108, 0xbfb8aa3b, v108
	v_mul_f32_e32 v100, 0xbfb8aa3b, v100
	global_store_dwordx4 v[116:117], v[112:115], off
	v_exp_f32_e32 v108, v108
	v_mul_f32_e32 v109, 0xbfb8aa3b, v109
	v_exp_f32_e32 v112, v100
	v_mul_f32_e32 v101, 0xbfb8aa3b, v101
	v_add_f32_e32 v100, 1.0, v108
	v_exp_f32_e32 v109, v109
	v_add_f32_e32 v108, 1.0, v112
	v_exp_f32_e32 v112, v101
	v_pk_mul_f32 v[110:111], v[110:111], v[192:193] op_sel_hi:[1,0]
	v_add_f32_e32 v101, 1.0, v109
	v_rcp_f32_e32 v108, v108
	v_add_f32_e32 v109, 1.0, v112
	v_rcp_f32_e32 v109, v109
	v_rcp_f32_e32 v100, v100
	v_rcp_f32_e32 v101, v101
	v_mul_f32_e32 v110, 0xbfb8aa3b, v110
	v_exp_f32_e32 v110, v110
	v_lshlrev_b32_e32 v114, 16, v128
	v_and_b32_e32 v115, 0xffff0000, v128
	v_pk_mul_f32 v[102:103], v[102:103], v[192:193] op_sel_hi:[1,0]
	v_lshlrev_b32_e32 v112, 16, v132
	v_and_b32_e32 v113, 0xffff0000, v132
	v_pk_mul_f32 v[108:109], v[108:109], v[114:115]
	v_mul_f32_e32 v102, 0xbfb8aa3b, v102
	v_pk_fma_f32 v[100:101], v[100:101], v[112:113], v[108:109]
	v_mul_f32_e32 v109, 0xbfb8aa3b, v111
	v_mul_f32_e32 v103, 0xbfb8aa3b, v103
	v_exp_f32_e32 v114, v102
	v_add_f32_e32 v102, 1.0, v110
	v_exp_f32_e32 v109, v109
	v_exp_f32_e32 v110, v103
	v_add_f32_e32 v108, 1.0, v114
	v_rcp_f32_e32 v108, v108
	v_add_f32_e32 v103, 1.0, v109
	v_add_f32_e32 v109, 1.0, v110
	v_rcp_f32_e32 v109, v109
	v_rcp_f32_e32 v102, v102
	v_rcp_f32_e32 v103, v103
	v_pk_mul_f32 v[104:105], v[104:105], v[192:193] op_sel_hi:[1,0]
	v_pk_mul_f32 v[96:97], v[96:97], v[192:193] op_sel_hi:[1,0]
	v_lshlrev_b32_e32 v112, 16, v129
	v_and_b32_e32 v113, 0xffff0000, v129
	v_lshlrev_b32_e32 v110, 16, v133
	v_and_b32_e32 v111, 0xffff0000, v133
	v_pk_mul_f32 v[108:109], v[108:109], v[112:113]
	v_mul_f32_e32 v104, 0xbfb8aa3b, v104
	v_mul_f32_e32 v96, 0xbfb8aa3b, v96
	v_mul_f32_e32 v105, 0xbfb8aa3b, v105
	v_mul_f32_e32 v97, 0xbfb8aa3b, v97
	v_exp_f32_e32 v104, v104
	v_exp_f32_e32 v112, v96
	v_pk_fma_f32 v[102:103], v[102:103], v[110:111], v[108:109]
	v_exp_f32_e32 v105, v105
	v_exp_f32_e32 v108, v97
	v_pk_mul_f32 v[98:99], v[98:99], v[192:193] op_sel_hi:[1,0]
	v_add_f32_e32 v96, 1.0, v104
	v_add_f32_e32 v104, 1.0, v112
	v_add_f32_e32 v97, 1.0, v105
	v_add_f32_e32 v105, 1.0, v108
	v_pk_mul_f32 v[106:107], v[106:107], v[192:193] op_sel_hi:[1,0]
	v_rcp_f32_e32 v104, v104
	v_rcp_f32_e32 v105, v105
	v_mul_f32_e32 v98, 0xbfb8aa3b, v98
	v_rcp_f32_e32 v96, v96
	v_rcp_f32_e32 v97, v97
	v_mul_f32_e32 v106, 0xbfb8aa3b, v106
	v_exp_f32_e32 v98, v98
	v_exp_f32_e32 v106, v106
	v_lshlrev_b32_e32 v110, 16, v130
	v_and_b32_e32 v111, 0xffff0000, v130
	v_lshlrev_b32_e32 v108, 16, v134
	v_and_b32_e32 v109, 0xffff0000, v134
	v_pk_mul_f32 v[104:105], v[104:105], v[110:111]
	v_lshlrev_b64 v[116:117], 11, v[160:161]
	v_pk_fma_f32 v[104:105], v[96:97], v[108:109], v[104:105]
	v_add_f32_e32 v97, 1.0, v98
	v_mul_f32_e32 v98, 0xbfb8aa3b, v107
	v_add_f32_e32 v96, 1.0, v106
	v_exp_f32_e32 v106, v98
	v_mul_f32_e32 v98, 0xbfb8aa3b, v99
	v_exp_f32_e32 v99, v98
	v_rcp_f32_e32 v98, v97
	v_add_f32_e32 v97, 1.0, v106
	v_rcp_f32_e32 v96, v96
	v_add_f32_e32 v99, 1.0, v99
	v_rcp_f32_e32 v99, v99
	v_rcp_f32_e32 v97, v97
	v_lshlrev_b32_e32 v108, 16, v131
	v_and_b32_e32 v109, 0xffff0000, v131
	v_lshlrev_b32_e32 v106, 16, v135
	v_and_b32_e32 v107, 0xffff0000, v135
	v_pk_mul_f32 v[98:99], v[98:99], v[108:109]
	s_nop 0
	v_pk_fma_f32 v[106:107], v[96:97], v[106:107], v[98:99]
	v_cvt_pk_bf16_f32 v96, v100, v101
	v_lshl_add_u64 v[100:101], s[50:51], 0, v[162:163]
	v_cvt_pk_bf16_f32 v97, v102, v103
	v_cvt_pk_bf16_f32 v98, v104, v105
	v_cvt_pk_bf16_f32 v99, v106, v107
	v_lshl_add_u64 v[100:101], v[100:101], 0, v[152:153]
	global_store_dwordx4 v[100:101], v[96:99], off
	v_add_u32_e32 v104, 0x80, v154
	v_ashrrev_i32_e32 v105, 31, v104
	v_lshl_add_u64 v[96:97], v[158:159], 0, v[116:117]
	global_load_dwordx4 v[108:111], v[96:97], off
	v_mad_i64_i32 v[96:97], s[8:9], v160, s61, v[156:157]
	global_load_dwordx4 v[112:115], v[96:97], off
	v_fmamk_f32 v96, v191, 0x3a800000, v170
	v_mul_f32_e32 v97, 0x4b800000, v96
	v_cmp_gt_f32_e32 vcc, s60, v96
	v_fmamk_f32 v98, v193, 0x3a800000, v170
	v_mul_f32_e32 v99, 0x4b800000, v98
	v_cndmask_b32_e32 v96, v96, v97, vcc
	v_rsq_f32_e32 v96, v96
	v_cmp_gt_f32_e64 s[8:9], s60, v98
	v_mul_f32_e32 v97, 0x45800000, v96
	s_nop 0
	v_cndmask_b32_e64 v98, v98, v99, s[8:9]
	v_rsq_f32_e32 v98, v98
	v_cndmask_b32_e32 v118, v96, v97, vcc
	v_or_b32_e32 v96, 48, v154
	v_ashrrev_i32_e32 v97, 31, v96
	v_mul_f32_e32 v99, 0x45800000, v98
	v_lshlrev_b64 v[106:107], 11, v[96:97]
	v_cndmask_b32_e64 v120, v98, v99, s[8:9]
	v_lshl_add_u64 v[98:99], v[158:159], 0, v[106:107]
	v_mad_i64_i32 v[96:97], s[8:9], v96, s61, v[156:157]
	global_load_dwordx4 v[100:103], v[98:99], off
	s_nop 0
	global_load_dwordx4 v[96:99], v[96:97], off
	v_pk_mul_f32 v[84:85], v[84:85], v[118:119] op_sel_hi:[1,0]
	v_pk_mul_f32 v[94:95], v[94:95], v[118:119] op_sel_hi:[1,0]
	v_mul_f32_e32 v84, 0xbfb8aa3b, v84
	v_pk_mul_f32 v[92:93], v[92:93], v[118:119] op_sel_hi:[1,0]
	v_pk_mul_f32 v[90:91], v[90:91], v[118:119] op_sel_hi:[1,0]
	v_pk_mul_f32 v[88:89], v[88:89], v[118:119] op_sel_hi:[1,0]
	v_pk_mul_f32 v[86:87], v[86:87], v[118:119] op_sel_hi:[1,0]
	v_pk_mul_f32 v[82:83], v[82:83], v[118:119] op_sel_hi:[1,0]
	v_exp_f32_e32 v119, v84
	v_mul_f32_e32 v92, 0xbfb8aa3b, v92
	v_mul_f32_e32 v93, 0xbfb8aa3b, v93
	v_mul_f32_e32 v85, 0xbfb8aa3b, v85
	v_exp_f32_e32 v92, v92
	v_pk_mul_f32 v[80:81], v[80:81], v[118:119] op_sel_hi:[1,0]
	v_exp_f32_e32 v93, v93
	v_exp_f32_e32 v118, v85
	v_add_f32_e32 v84, 1.0, v92
	v_add_f32_e32 v92, 1.0, v119
	v_add_f32_e32 v85, 1.0, v93
	v_add_f32_e32 v93, 1.0, v118
	v_rcp_f32_e32 v92, v92
	v_rcp_f32_e32 v93, v93
	v_rcp_f32_e32 v84, v84
	v_rcp_f32_e32 v85, v85
	v_mul_f32_e32 v94, 0xbfb8aa3b, v94
	v_exp_f32_e32 v94, v94
	v_mul_f32_e32 v86, 0xbfb8aa3b, v86
	v_mul_f32_e32 v87, 0xbfb8aa3b, v87
	v_mul_f32_e32 v88, 0xbfb8aa3b, v88
	v_mul_f32_e32 v80, 0xbfb8aa3b, v80
	v_mul_f32_e32 v89, 0xbfb8aa3b, v89
	v_mul_f32_e32 v81, 0xbfb8aa3b, v81
	v_exp_f32_e32 v88, v88
	v_exp_f32_e32 v89, v89
	v_mul_f32_e32 v82, 0xbfb8aa3b, v82
	v_mul_f32_e32 v90, 0xbfb8aa3b, v90
	v_exp_f32_e32 v82, v82
	v_exp_f32_e32 v90, v90
	v_pk_mul_f32 v[76:77], v[76:77], v[120:121] op_sel_hi:[1,0]
	v_pk_mul_f32 v[68:69], v[68:69], v[120:121] op_sel_hi:[1,0]
	v_mul_f32_e32 v76, 0xbfb8aa3b, v76
	v_mul_f32_e32 v68, 0xbfb8aa3b, v68
	v_exp_f32_e32 v76, v76
	v_mul_f32_e32 v77, 0xbfb8aa3b, v77
	v_mul_f32_e32 v69, 0xbfb8aa3b, v69
	v_exp_f32_e32 v77, v77
	v_pk_mul_f32 v[78:79], v[78:79], v[120:121] op_sel_hi:[1,0]
	v_pk_mul_f32 v[70:71], v[70:71], v[120:121] op_sel_hi:[1,0]
	v_mul_f32_e32 v78, 0xbfb8aa3b, v78
	v_exp_f32_e32 v78, v78
	v_mul_f32_e32 v70, 0xbfb8aa3b, v70
	v_mul_f32_e32 v71, 0xbfb8aa3b, v71
	v_pk_mul_f32 v[72:73], v[72:73], v[120:121] op_sel_hi:[1,0]
	s_waitcnt vmcnt(3)
	v_lshlrev_b32_e32 v118, 16, v108
	v_and_b32_e32 v119, 0xffff0000, v108
	v_exp_f32_e32 v108, v86
	s_waitcnt vmcnt(2)
	v_lshlrev_b32_e32 v122, 16, v112
	v_and_b32_e32 v123, 0xffff0000, v112
	v_pk_mul_f32 v[92:93], v[92:93], v[122:123]
	v_add_f32_e32 v86, 1.0, v94
	v_pk_fma_f32 v[84:85], v[84:85], v[118:119], v[92:93]
	v_mul_f32_e32 v93, 0xbfb8aa3b, v95
	v_exp_f32_e32 v93, v93
	v_exp_f32_e32 v94, v87
	v_add_f32_e32 v92, 1.0, v108
	v_rcp_f32_e32 v92, v92
	v_add_f32_e32 v87, 1.0, v93
	v_add_f32_e32 v93, 1.0, v94
	v_rcp_f32_e32 v93, v93
	v_rcp_f32_e32 v86, v86
	v_rcp_f32_e32 v87, v87
	v_lshlrev_b32_e32 v94, 16, v109
	v_and_b32_e32 v95, 0xffff0000, v109
	v_lshlrev_b32_e32 v108, 16, v113
	v_and_b32_e32 v109, 0xffff0000, v113
	v_pk_mul_f32 v[92:93], v[92:93], v[108:109]
	v_exp_f32_e32 v108, v80
	v_pk_fma_f32 v[86:87], v[86:87], v[94:95], v[92:93]
	v_exp_f32_e32 v92, v81
	v_add_f32_e32 v80, 1.0, v88
	v_add_f32_e32 v88, 1.0, v108
	v_add_f32_e32 v81, 1.0, v89
	v_add_f32_e32 v89, 1.0, v92
	v_rcp_f32_e32 v88, v88
	v_rcp_f32_e32 v89, v89
	v_rcp_f32_e32 v80, v80
	v_rcp_f32_e32 v81, v81
	v_lshlrev_b32_e32 v94, 16, v114
	v_and_b32_e32 v95, 0xffff0000, v114
	v_lshlrev_b32_e32 v92, 16, v110
	v_and_b32_e32 v93, 0xffff0000, v110
	v_pk_mul_f32 v[88:89], v[88:89], v[94:95]
	v_pk_mul_f32 v[64:65], v[64:65], v[120:121] op_sel_hi:[1,0]
	v_pk_fma_f32 v[88:89], v[80:81], v[92:93], v[88:89]
	v_add_f32_e32 v81, 1.0, v82
	v_mul_f32_e32 v82, 0xbfb8aa3b, v91
	v_add_f32_e32 v80, 1.0, v90
	v_exp_f32_e32 v90, v82
	v_mul_f32_e32 v82, 0xbfb8aa3b, v83
	v_exp_f32_e32 v83, v82
	v_rcp_f32_e32 v82, v81
	v_add_f32_e32 v81, 1.0, v90
	v_rcp_f32_e32 v80, v80
	v_add_f32_e32 v83, 1.0, v83
	v_rcp_f32_e32 v83, v83
	v_rcp_f32_e32 v81, v81
	v_lshlrev_b32_e32 v92, 16, v115
	v_and_b32_e32 v93, 0xffff0000, v115
	v_lshlrev_b32_e32 v90, 16, v111
	v_and_b32_e32 v91, 0xffff0000, v111
	v_pk_mul_f32 v[82:83], v[82:83], v[92:93]
	v_mul_f32_e32 v72, 0xbfb8aa3b, v72
	v_pk_fma_f32 v[90:91], v[80:81], v[90:91], v[82:83]
	v_cvt_pk_bf16_f32 v80, v84, v85
	v_lshl_add_u64 v[84:85], s[50:51], 0, v[116:117]
	v_cvt_pk_bf16_f32 v81, v86, v87
	v_cvt_pk_bf16_f32 v82, v88, v89
	v_cvt_pk_bf16_f32 v83, v90, v91
	v_lshl_add_u64 v[84:85], v[84:85], 0, v[152:153]
	global_store_dwordx4 v[84:85], v[80:83], off
	v_mul_f32_e32 v64, 0xbfb8aa3b, v64
	v_mul_f32_e32 v73, 0xbfb8aa3b, v73
	v_exp_f32_e32 v80, v68
	v_add_f32_e32 v68, 1.0, v76
	v_rcp_f32_e32 v68, v68
	s_waitcnt vmcnt(1)
	v_lshlrev_b32_e32 v82, 16, v96
	v_add_f32_e32 v76, 1.0, v80
	v_exp_f32_e32 v80, v69
	v_add_f32_e32 v69, 1.0, v77
	v_rcp_f32_e32 v76, v76
	v_rcp_f32_e32 v69, v69
	v_add_f32_e32 v77, 1.0, v80
	v_rcp_f32_e32 v77, v77
	v_and_b32_e32 v83, 0xffff0000, v96
	v_lshlrev_b32_e32 v80, 16, v100
	v_and_b32_e32 v81, 0xffff0000, v100
	v_pk_mul_f32 v[76:77], v[76:77], v[82:83]
	v_exp_f32_e32 v82, v70
	v_pk_fma_f32 v[68:69], v[68:69], v[80:81], v[76:77]
	v_mul_f32_e32 v77, 0xbfb8aa3b, v79
	v_add_f32_e32 v70, 1.0, v78
	v_exp_f32_e32 v77, v77
	v_exp_f32_e32 v78, v71
	v_add_f32_e32 v76, 1.0, v82
	v_rcp_f32_e32 v76, v76
	v_add_f32_e32 v71, 1.0, v77
	v_add_f32_e32 v77, 1.0, v78
	v_rcp_f32_e32 v77, v77
	v_rcp_f32_e32 v70, v70
	v_rcp_f32_e32 v71, v71
	v_lshlrev_b32_e32 v80, 16, v97
	v_and_b32_e32 v81, 0xffff0000, v97
	v_lshlrev_b32_e32 v78, 16, v101
	v_and_b32_e32 v79, 0xffff0000, v101
	v_pk_mul_f32 v[76:77], v[76:77], v[80:81]
	v_mul_f32_e32 v65, 0xbfb8aa3b, v65
	v_exp_f32_e32 v72, v72
	v_exp_f32_e32 v80, v64
	v_pk_fma_f32 v[70:71], v[70:71], v[78:79], v[76:77]
	v_exp_f32_e32 v73, v73
	v_exp_f32_e32 v76, v65
	v_pk_mul_f32 v[66:67], v[66:67], v[120:121] op_sel_hi:[1,0]
	v_add_f32_e32 v64, 1.0, v72
	v_add_f32_e32 v72, 1.0, v80
	v_add_f32_e32 v65, 1.0, v73
	v_add_f32_e32 v73, 1.0, v76
	v_pk_mul_f32 v[74:75], v[74:75], v[120:121] op_sel_hi:[1,0]
	v_rcp_f32_e32 v72, v72
	v_rcp_f32_e32 v73, v73
	v_mul_f32_e32 v66, 0xbfb8aa3b, v66
	v_rcp_f32_e32 v64, v64
	v_rcp_f32_e32 v65, v65
	v_mul_f32_e32 v74, 0xbfb8aa3b, v74
	v_exp_f32_e32 v66, v66
	v_exp_f32_e32 v74, v74
	v_lshlrev_b32_e32 v78, 16, v98
	v_and_b32_e32 v79, 0xffff0000, v98
	v_lshlrev_b32_e32 v76, 16, v102
	v_and_b32_e32 v77, 0xffff0000, v102
	v_pk_mul_f32 v[72:73], v[72:73], v[78:79]
	v_lshlrev_b64 v[84:85], 11, v[104:105]
	v_pk_fma_f32 v[72:73], v[64:65], v[76:77], v[72:73]
	v_add_f32_e32 v65, 1.0, v66
	v_mul_f32_e32 v66, 0xbfb8aa3b, v75
	v_add_f32_e32 v64, 1.0, v74
	v_exp_f32_e32 v74, v66
	v_mul_f32_e32 v66, 0xbfb8aa3b, v67
	v_exp_f32_e32 v67, v66
	v_rcp_f32_e32 v66, v65
	v_add_f32_e32 v65, 1.0, v74
	v_rcp_f32_e32 v64, v64
	v_add_f32_e32 v67, 1.0, v67
	v_rcp_f32_e32 v67, v67
	v_rcp_f32_e32 v65, v65
	v_lshlrev_b32_e32 v76, 16, v99
	v_and_b32_e32 v77, 0xffff0000, v99
	v_lshlrev_b32_e32 v74, 16, v103
	v_and_b32_e32 v75, 0xffff0000, v103
	v_pk_mul_f32 v[66:67], v[66:67], v[76:77]
	s_nop 0
	v_pk_fma_f32 v[74:75], v[64:65], v[74:75], v[66:67]
	v_cvt_pk_bf16_f32 v64, v68, v69
	v_lshl_add_u64 v[68:69], s[50:51], 0, v[106:107]
	v_cvt_pk_bf16_f32 v65, v70, v71
	v_cvt_pk_bf16_f32 v66, v72, v73
	v_cvt_pk_bf16_f32 v67, v74, v75
	v_lshl_add_u64 v[68:69], v[68:69], 0, v[152:153]
	global_store_dwordx4 v[68:69], v[64:67], off
	v_add_u32_e32 v72, 0xa0, v154
	v_ashrrev_i32_e32 v73, 31, v72
	v_lshl_add_u64 v[64:65], v[158:159], 0, v[84:85]
	global_load_dwordx4 v[76:79], v[64:65], off
	v_mad_i64_i32 v[64:65], s[8:9], v104, s61, v[156:157]
	global_load_dwordx4 v[80:83], v[64:65], off
	v_fmamk_f32 v64, v173, 0x3a800000, v170
	v_mul_f32_e32 v65, 0x4b800000, v64
	v_cmp_gt_f32_e32 vcc, s60, v64
	v_fmamk_f32 v66, v174, 0x3a800000, v170
	v_mul_f32_e32 v67, 0x4b800000, v66
	v_cndmask_b32_e32 v64, v64, v65, vcc
	v_rsq_f32_e32 v64, v64
	v_cmp_gt_f32_e64 s[8:9], s60, v66
	v_mul_f32_e32 v65, 0x45800000, v64
	s_nop 0
	v_cndmask_b32_e64 v66, v66, v67, s[8:9]
	v_rsq_f32_e32 v66, v66
	v_cndmask_b32_e32 v86, v64, v65, vcc
	v_add_u32_e32 v64, 0x90, v154
	v_ashrrev_i32_e32 v65, 31, v64
	v_mul_f32_e32 v67, 0x45800000, v66
	v_lshlrev_b64 v[74:75], 11, v[64:65]
	v_cndmask_b32_e64 v88, v66, v67, s[8:9]
	v_lshl_add_u64 v[66:67], v[158:159], 0, v[74:75]
	v_mad_i64_i32 v[64:65], s[8:9], v64, s61, v[156:157]
	global_load_dwordx4 v[68:71], v[66:67], off
	s_nop 0
	global_load_dwordx4 v[64:67], v[64:65], off
	v_pk_mul_f32 v[52:53], v[52:53], v[86:87] op_sel_hi:[1,0]
	v_pk_mul_f32 v[62:63], v[62:63], v[86:87] op_sel_hi:[1,0]
	v_mul_f32_e32 v52, 0xbfb8aa3b, v52
	v_pk_mul_f32 v[60:61], v[60:61], v[86:87] op_sel_hi:[1,0]
	v_pk_mul_f32 v[58:59], v[58:59], v[86:87] op_sel_hi:[1,0]
	v_pk_mul_f32 v[56:57], v[56:57], v[86:87] op_sel_hi:[1,0]
	v_pk_mul_f32 v[54:55], v[54:55], v[86:87] op_sel_hi:[1,0]
	v_pk_mul_f32 v[50:51], v[50:51], v[86:87] op_sel_hi:[1,0]
	v_exp_f32_e32 v87, v52
	v_mul_f32_e32 v60, 0xbfb8aa3b, v60
	v_mul_f32_e32 v61, 0xbfb8aa3b, v61
	v_mul_f32_e32 v53, 0xbfb8aa3b, v53
	v_exp_f32_e32 v60, v60
	v_pk_mul_f32 v[48:49], v[48:49], v[86:87] op_sel_hi:[1,0]
	v_exp_f32_e32 v61, v61
	v_exp_f32_e32 v86, v53
	v_add_f32_e32 v52, 1.0, v60
	v_add_f32_e32 v60, 1.0, v87
	v_add_f32_e32 v53, 1.0, v61
	v_add_f32_e32 v61, 1.0, v86
	v_rcp_f32_e32 v60, v60
	v_rcp_f32_e32 v61, v61
	v_rcp_f32_e32 v52, v52
	v_rcp_f32_e32 v53, v53
	v_mul_f32_e32 v62, 0xbfb8aa3b, v62
	v_exp_f32_e32 v62, v62
	v_mul_f32_e32 v54, 0xbfb8aa3b, v54
	v_mul_f32_e32 v55, 0xbfb8aa3b, v55
	v_mul_f32_e32 v56, 0xbfb8aa3b, v56
	v_mul_f32_e32 v48, 0xbfb8aa3b, v48
	v_mul_f32_e32 v57, 0xbfb8aa3b, v57
	v_mul_f32_e32 v49, 0xbfb8aa3b, v49
	v_exp_f32_e32 v56, v56
	v_exp_f32_e32 v57, v57
	v_mul_f32_e32 v50, 0xbfb8aa3b, v50
	v_mul_f32_e32 v58, 0xbfb8aa3b, v58
	v_exp_f32_e32 v50, v50
	v_exp_f32_e32 v58, v58
	v_pk_mul_f32 v[44:45], v[44:45], v[88:89] op_sel_hi:[1,0]
	v_pk_mul_f32 v[36:37], v[36:37], v[88:89] op_sel_hi:[1,0]
	v_mul_f32_e32 v44, 0xbfb8aa3b, v44
	v_mul_f32_e32 v36, 0xbfb8aa3b, v36
	v_exp_f32_e32 v44, v44
	v_mul_f32_e32 v45, 0xbfb8aa3b, v45
	v_mul_f32_e32 v37, 0xbfb8aa3b, v37
	v_exp_f32_e32 v45, v45
	v_pk_mul_f32 v[46:47], v[46:47], v[88:89] op_sel_hi:[1,0]
	v_pk_mul_f32 v[38:39], v[38:39], v[88:89] op_sel_hi:[1,0]
	v_mul_f32_e32 v46, 0xbfb8aa3b, v46
	v_exp_f32_e32 v46, v46
	v_mul_f32_e32 v38, 0xbfb8aa3b, v38
	v_mul_f32_e32 v39, 0xbfb8aa3b, v39
	v_pk_mul_f32 v[40:41], v[40:41], v[88:89] op_sel_hi:[1,0]
	s_waitcnt vmcnt(3)
	v_lshlrev_b32_e32 v86, 16, v76
	v_and_b32_e32 v87, 0xffff0000, v76
	v_exp_f32_e32 v76, v54
	s_waitcnt vmcnt(2)
	v_lshlrev_b32_e32 v90, 16, v80
	v_and_b32_e32 v91, 0xffff0000, v80
	v_pk_mul_f32 v[60:61], v[60:61], v[90:91]
	v_add_f32_e32 v54, 1.0, v62
	v_pk_fma_f32 v[52:53], v[52:53], v[86:87], v[60:61]
	v_mul_f32_e32 v61, 0xbfb8aa3b, v63
	v_exp_f32_e32 v61, v61
	v_exp_f32_e32 v62, v55
	v_add_f32_e32 v60, 1.0, v76
	v_rcp_f32_e32 v60, v60
	v_add_f32_e32 v55, 1.0, v61
	v_add_f32_e32 v61, 1.0, v62
	v_rcp_f32_e32 v61, v61
	v_rcp_f32_e32 v54, v54
	v_rcp_f32_e32 v55, v55
	v_lshlrev_b32_e32 v62, 16, v77
	v_and_b32_e32 v63, 0xffff0000, v77
	v_lshlrev_b32_e32 v76, 16, v81
	v_and_b32_e32 v77, 0xffff0000, v81
	v_pk_mul_f32 v[60:61], v[60:61], v[76:77]
	v_exp_f32_e32 v76, v48
	v_pk_fma_f32 v[54:55], v[54:55], v[62:63], v[60:61]
	v_exp_f32_e32 v60, v49
	v_add_f32_e32 v48, 1.0, v56
	v_add_f32_e32 v56, 1.0, v76
	v_add_f32_e32 v49, 1.0, v57
	v_add_f32_e32 v57, 1.0, v60
	v_rcp_f32_e32 v56, v56
	v_rcp_f32_e32 v57, v57
	v_rcp_f32_e32 v48, v48
	v_rcp_f32_e32 v49, v49
	v_lshlrev_b32_e32 v62, 16, v82
	v_and_b32_e32 v63, 0xffff0000, v82
	v_lshlrev_b32_e32 v60, 16, v78
	v_and_b32_e32 v61, 0xffff0000, v78
	v_pk_mul_f32 v[56:57], v[56:57], v[62:63]
	v_pk_mul_f32 v[32:33], v[32:33], v[88:89] op_sel_hi:[1,0]
	v_pk_fma_f32 v[56:57], v[48:49], v[60:61], v[56:57]
	v_add_f32_e32 v49, 1.0, v50
	v_mul_f32_e32 v50, 0xbfb8aa3b, v59
	v_add_f32_e32 v48, 1.0, v58
	v_exp_f32_e32 v58, v50
	v_mul_f32_e32 v50, 0xbfb8aa3b, v51
	v_exp_f32_e32 v51, v50
	v_rcp_f32_e32 v50, v49
	v_add_f32_e32 v49, 1.0, v58
	v_rcp_f32_e32 v48, v48
	v_add_f32_e32 v51, 1.0, v51
	v_rcp_f32_e32 v51, v51
	v_rcp_f32_e32 v49, v49
	v_lshlrev_b32_e32 v60, 16, v83
	v_and_b32_e32 v61, 0xffff0000, v83
	v_lshlrev_b32_e32 v58, 16, v79
	v_and_b32_e32 v59, 0xffff0000, v79
	v_pk_mul_f32 v[50:51], v[50:51], v[60:61]
	v_mul_f32_e32 v40, 0xbfb8aa3b, v40
	v_pk_fma_f32 v[58:59], v[48:49], v[58:59], v[50:51]
	v_cvt_pk_bf16_f32 v48, v52, v53
	v_lshl_add_u64 v[52:53], s[50:51], 0, v[84:85]
	v_cvt_pk_bf16_f32 v49, v54, v55
	v_cvt_pk_bf16_f32 v50, v56, v57
	v_cvt_pk_bf16_f32 v51, v58, v59
	v_lshl_add_u64 v[52:53], v[52:53], 0, v[152:153]
	global_store_dwordx4 v[52:53], v[48:51], off
	v_mul_f32_e32 v32, 0xbfb8aa3b, v32
	v_mul_f32_e32 v41, 0xbfb8aa3b, v41
	v_exp_f32_e32 v48, v36
	v_add_f32_e32 v36, 1.0, v44
	v_rcp_f32_e32 v36, v36
	s_waitcnt vmcnt(1)
	v_lshlrev_b32_e32 v50, 16, v64
	v_add_f32_e32 v44, 1.0, v48
	v_exp_f32_e32 v48, v37
	v_add_f32_e32 v37, 1.0, v45
	v_rcp_f32_e32 v44, v44
	v_rcp_f32_e32 v37, v37
	v_add_f32_e32 v45, 1.0, v48
	v_rcp_f32_e32 v45, v45
	v_and_b32_e32 v51, 0xffff0000, v64
	v_lshlrev_b32_e32 v48, 16, v68
	v_and_b32_e32 v49, 0xffff0000, v68
	v_pk_mul_f32 v[44:45], v[44:45], v[50:51]
	v_exp_f32_e32 v50, v38
	v_pk_fma_f32 v[36:37], v[36:37], v[48:49], v[44:45]
	v_mul_f32_e32 v45, 0xbfb8aa3b, v47
	v_add_f32_e32 v38, 1.0, v46
	v_exp_f32_e32 v45, v45
	v_exp_f32_e32 v46, v39
	v_add_f32_e32 v44, 1.0, v50
	v_rcp_f32_e32 v44, v44
	v_add_f32_e32 v39, 1.0, v45
	v_add_f32_e32 v45, 1.0, v46
	v_rcp_f32_e32 v45, v45
	v_rcp_f32_e32 v38, v38
	v_rcp_f32_e32 v39, v39
	v_lshlrev_b32_e32 v48, 16, v65
	v_and_b32_e32 v49, 0xffff0000, v65
	v_lshlrev_b32_e32 v46, 16, v69
	v_and_b32_e32 v47, 0xffff0000, v69
	v_pk_mul_f32 v[44:45], v[44:45], v[48:49]
	v_mul_f32_e32 v33, 0xbfb8aa3b, v33
	v_exp_f32_e32 v40, v40
	v_exp_f32_e32 v48, v32
	v_pk_fma_f32 v[38:39], v[38:39], v[46:47], v[44:45]
	v_exp_f32_e32 v41, v41
	v_exp_f32_e32 v44, v33
	v_pk_mul_f32 v[34:35], v[34:35], v[88:89] op_sel_hi:[1,0]
	v_add_f32_e32 v32, 1.0, v40
	v_add_f32_e32 v40, 1.0, v48
	v_add_f32_e32 v33, 1.0, v41
	v_add_f32_e32 v41, 1.0, v44
	v_pk_mul_f32 v[42:43], v[42:43], v[88:89] op_sel_hi:[1,0]
	v_rcp_f32_e32 v40, v40
	v_rcp_f32_e32 v41, v41
	v_mul_f32_e32 v34, 0xbfb8aa3b, v34
	v_rcp_f32_e32 v32, v32
	v_rcp_f32_e32 v33, v33
	v_mul_f32_e32 v42, 0xbfb8aa3b, v42
	v_exp_f32_e32 v34, v34
	v_exp_f32_e32 v42, v42
	v_lshlrev_b32_e32 v46, 16, v66
	v_and_b32_e32 v47, 0xffff0000, v66
	v_lshlrev_b32_e32 v44, 16, v70
	v_and_b32_e32 v45, 0xffff0000, v70
	v_pk_mul_f32 v[40:41], v[40:41], v[46:47]
	v_lshlrev_b64 v[50:51], 11, v[72:73]
	v_pk_fma_f32 v[40:41], v[32:33], v[44:45], v[40:41]
	v_add_f32_e32 v33, 1.0, v34
	v_mul_f32_e32 v34, 0xbfb8aa3b, v43
	v_add_f32_e32 v32, 1.0, v42
	v_exp_f32_e32 v42, v34
	v_mul_f32_e32 v34, 0xbfb8aa3b, v35
	v_exp_f32_e32 v35, v34
	v_rcp_f32_e32 v34, v33
	v_add_f32_e32 v33, 1.0, v42
	v_rcp_f32_e32 v32, v32
	v_add_f32_e32 v35, 1.0, v35
	v_rcp_f32_e32 v35, v35
	v_rcp_f32_e32 v33, v33
	v_lshlrev_b32_e32 v44, 16, v67
	v_and_b32_e32 v45, 0xffff0000, v67
	v_lshlrev_b32_e32 v42, 16, v71
	v_and_b32_e32 v43, 0xffff0000, v71
	v_pk_mul_f32 v[34:35], v[34:35], v[44:45]
	s_nop 0
	v_pk_fma_f32 v[42:43], v[32:33], v[42:43], v[34:35]
	v_cvt_pk_bf16_f32 v32, v36, v37
	v_lshl_add_u64 v[36:37], s[50:51], 0, v[74:75]
	v_cvt_pk_bf16_f32 v33, v38, v39
	v_cvt_pk_bf16_f32 v34, v40, v41
	v_cvt_pk_bf16_f32 v35, v42, v43
	v_lshl_add_u64 v[36:37], v[36:37], 0, v[152:153]
	global_store_dwordx4 v[36:37], v[32:35], off
	s_nop 1
	v_lshl_add_u64 v[32:33], v[158:159], 0, v[50:51]
	global_load_dwordx4 v[42:45], v[32:33], off
	v_mad_i64_i32 v[32:33], s[8:9], v72, s61, v[156:157]
	global_load_dwordx4 v[46:49], v[32:33], off
	v_fmamk_f32 v32, v171, 0x3a800000, v170
	v_mul_f32_e32 v33, 0x4b800000, v32
	v_cmp_gt_f32_e32 vcc, s60, v32
	v_fmamk_f32 v34, v172, 0x3a800000, v170
	v_mul_f32_e32 v35, 0x4b800000, v34
	v_cndmask_b32_e32 v32, v32, v33, vcc
	v_rsq_f32_e32 v32, v32
	v_cmp_gt_f32_e64 s[8:9], s60, v34
	v_mul_f32_e32 v33, 0x45800000, v32
	s_nop 0
	v_cndmask_b32_e64 v34, v34, v35, s[8:9]
	v_rsq_f32_e32 v34, v34
	v_cndmask_b32_e32 v52, v32, v33, vcc
	v_add_u32_e32 v32, 0xb0, v154
	v_ashrrev_i32_e32 v33, 31, v32
	v_mul_f32_e32 v35, 0x45800000, v34
	v_lshlrev_b64 v[40:41], 11, v[32:33]
	v_cndmask_b32_e64 v54, v34, v35, s[8:9]
	v_lshl_add_u64 v[34:35], v[158:159], 0, v[40:41]
	v_mad_i64_i32 v[32:33], s[8:9], v32, s61, v[156:157]
	global_load_dwordx4 v[36:39], v[34:35], off
	s_nop 0
	global_load_dwordx4 v[32:35], v[32:33], off
	v_pk_mul_f32 v[20:21], v[20:21], v[52:53] op_sel_hi:[1,0]
	v_pk_mul_f32 v[30:31], v[30:31], v[52:53] op_sel_hi:[1,0]
	v_mul_f32_e32 v20, 0xbfb8aa3b, v20
	v_pk_mul_f32 v[28:29], v[28:29], v[52:53] op_sel_hi:[1,0]
	v_pk_mul_f32 v[26:27], v[26:27], v[52:53] op_sel_hi:[1,0]
	v_pk_mul_f32 v[24:25], v[24:25], v[52:53] op_sel_hi:[1,0]
	v_pk_mul_f32 v[22:23], v[22:23], v[52:53] op_sel_hi:[1,0]
	v_pk_mul_f32 v[18:19], v[18:19], v[52:53] op_sel_hi:[1,0]
	v_exp_f32_e32 v53, v20
	v_mul_f32_e32 v28, 0xbfb8aa3b, v28
	v_mul_f32_e32 v29, 0xbfb8aa3b, v29
	v_mul_f32_e32 v21, 0xbfb8aa3b, v21
	v_exp_f32_e32 v28, v28
	v_pk_mul_f32 v[16:17], v[16:17], v[52:53] op_sel_hi:[1,0]
	v_exp_f32_e32 v29, v29
	v_exp_f32_e32 v52, v21
	v_add_f32_e32 v20, 1.0, v28
	v_add_f32_e32 v28, 1.0, v53
	v_add_f32_e32 v21, 1.0, v29
	v_add_f32_e32 v29, 1.0, v52
	v_rcp_f32_e32 v28, v28
	v_rcp_f32_e32 v29, v29
	v_rcp_f32_e32 v20, v20
	v_rcp_f32_e32 v21, v21
	v_mul_f32_e32 v30, 0xbfb8aa3b, v30
	v_exp_f32_e32 v30, v30
	v_mul_f32_e32 v22, 0xbfb8aa3b, v22
	v_mul_f32_e32 v23, 0xbfb8aa3b, v23
	v_mul_f32_e32 v24, 0xbfb8aa3b, v24
	v_mul_f32_e32 v16, 0xbfb8aa3b, v16
	v_mul_f32_e32 v25, 0xbfb8aa3b, v25
	v_mul_f32_e32 v17, 0xbfb8aa3b, v17
	v_exp_f32_e32 v24, v24
	v_exp_f32_e32 v25, v25
	v_mul_f32_e32 v18, 0xbfb8aa3b, v18
	v_mul_f32_e32 v26, 0xbfb8aa3b, v26
	v_exp_f32_e32 v18, v18
	v_exp_f32_e32 v26, v26
	v_pk_mul_f32 v[12:13], v[12:13], v[54:55] op_sel_hi:[1,0]
	v_pk_mul_f32 v[4:5], v[4:5], v[54:55] op_sel_hi:[1,0]
	v_mul_f32_e32 v12, 0xbfb8aa3b, v12
	v_mul_f32_e32 v4, 0xbfb8aa3b, v4
	v_exp_f32_e32 v12, v12
	v_mul_f32_e32 v13, 0xbfb8aa3b, v13
	v_mul_f32_e32 v5, 0xbfb8aa3b, v5
	v_exp_f32_e32 v13, v13
	v_pk_mul_f32 v[14:15], v[14:15], v[54:55] op_sel_hi:[1,0]
	v_pk_mul_f32 v[6:7], v[6:7], v[54:55] op_sel_hi:[1,0]
	v_mul_f32_e32 v14, 0xbfb8aa3b, v14
	v_exp_f32_e32 v14, v14
	v_mul_f32_e32 v6, 0xbfb8aa3b, v6
	v_mul_f32_e32 v7, 0xbfb8aa3b, v7
	v_pk_mul_f32 v[8:9], v[8:9], v[54:55] op_sel_hi:[1,0]
	s_waitcnt vmcnt(3)
; #define PG8_BAR __builtin_amdgcn_s_barrier()
; template <class Epi, class Sched, bool ALIGN_EPI = false, bool SP2 = false>
; __device__ __forceinline__ void gemm_phase(LAS unsigned char* lds, const Gemm g, const Sched S, const Epi E) {
;     ...
;         if (!has_next) break;
; #pragma unroll
;         for (int a = 0; a < 2; ++a)
; #pragma unroll
;             for (int b = 0; b < 2; ++b)
; #pragma unroll
;                 for (int m = 0; m < 4; ++m)
; #pragma unroll
;                     for (int n = 0; n < 2; ++n) acc[a][b][m][n] = (f32x4){0.f, 0.f, 0.f, 0.f};
;         cur = nxt; cA = nA; cB = nB; ++ui;
;         if constexpr (ALIGN_EPI) { if (wr == 1) PG8_BAR; }
	v_lshlrev_b32_e32 v52, 16, v42
	v_and_b32_e32 v53, 0xffff0000, v42
	v_exp_f32_e32 v42, v22
	s_waitcnt vmcnt(2)
	v_lshlrev_b32_e32 v56, 16, v46
	v_and_b32_e32 v57, 0xffff0000, v46
	v_pk_mul_f32 v[28:29], v[28:29], v[56:57]
	v_add_f32_e32 v22, 1.0, v30
	v_pk_fma_f32 v[20:21], v[20:21], v[52:53], v[28:29]
	v_mul_f32_e32 v29, 0xbfb8aa3b, v31
	v_exp_f32_e32 v29, v29
	v_exp_f32_e32 v30, v23
	v_add_f32_e32 v28, 1.0, v42
	v_rcp_f32_e32 v28, v28
	v_add_f32_e32 v23, 1.0, v29
	v_add_f32_e32 v29, 1.0, v30
	v_rcp_f32_e32 v29, v29
	v_rcp_f32_e32 v22, v22
	v_rcp_f32_e32 v23, v23
	v_lshlrev_b32_e32 v30, 16, v43
	v_and_b32_e32 v31, 0xffff0000, v43
	v_lshlrev_b32_e32 v42, 16, v47
	v_and_b32_e32 v43, 0xffff0000, v47
	v_pk_mul_f32 v[28:29], v[28:29], v[42:43]
	v_exp_f32_e32 v42, v16
	v_pk_fma_f32 v[22:23], v[22:23], v[30:31], v[28:29]
	v_exp_f32_e32 v28, v17
	v_add_f32_e32 v16, 1.0, v24
	v_add_f32_e32 v24, 1.0, v42
	v_add_f32_e32 v17, 1.0, v25
	v_add_f32_e32 v25, 1.0, v28
	v_rcp_f32_e32 v24, v24
	v_rcp_f32_e32 v25, v25
	v_rcp_f32_e32 v16, v16
	v_rcp_f32_e32 v17, v17
	v_lshlrev_b32_e32 v30, 16, v48
	v_and_b32_e32 v31, 0xffff0000, v48
	v_lshlrev_b32_e32 v28, 16, v44
	v_and_b32_e32 v29, 0xffff0000, v44
	v_pk_mul_f32 v[24:25], v[24:25], v[30:31]
	v_pk_mul_f32 v[0:1], v[0:1], v[54:55] op_sel_hi:[1,0]
	v_pk_fma_f32 v[24:25], v[16:17], v[28:29], v[24:25]
	v_add_f32_e32 v17, 1.0, v18
	v_mul_f32_e32 v18, 0xbfb8aa3b, v27
	v_add_f32_e32 v16, 1.0, v26
	v_exp_f32_e32 v26, v18
	v_mul_f32_e32 v18, 0xbfb8aa3b, v19
	v_exp_f32_e32 v19, v18
	v_rcp_f32_e32 v18, v17
	v_add_f32_e32 v17, 1.0, v26
	v_rcp_f32_e32 v16, v16
	v_add_f32_e32 v19, 1.0, v19
	v_rcp_f32_e32 v19, v19
	v_rcp_f32_e32 v17, v17
	v_lshlrev_b32_e32 v28, 16, v49
	v_and_b32_e32 v29, 0xffff0000, v49
	v_lshlrev_b32_e32 v26, 16, v45
	v_and_b32_e32 v27, 0xffff0000, v45
	v_pk_mul_f32 v[18:19], v[18:19], v[28:29]
	v_mul_f32_e32 v8, 0xbfb8aa3b, v8
	v_pk_fma_f32 v[26:27], v[16:17], v[26:27], v[18:19]
	v_cvt_pk_bf16_f32 v16, v20, v21
	v_lshl_add_u64 v[20:21], s[50:51], 0, v[50:51]
	v_cvt_pk_bf16_f32 v17, v22, v23
	v_cvt_pk_bf16_f32 v18, v24, v25
	v_cvt_pk_bf16_f32 v19, v26, v27
	v_lshl_add_u64 v[20:21], v[20:21], 0, v[152:153]
	global_store_dwordx4 v[20:21], v[16:19], off
	v_mul_f32_e32 v0, 0xbfb8aa3b, v0
	v_mul_f32_e32 v9, 0xbfb8aa3b, v9
	v_exp_f32_e32 v16, v4
	v_add_f32_e32 v4, 1.0, v12
	v_rcp_f32_e32 v4, v4
	s_waitcnt vmcnt(1)
	v_lshlrev_b32_e32 v18, 16, v32
	v_add_f32_e32 v12, 1.0, v16
	v_exp_f32_e32 v16, v5
	v_add_f32_e32 v5, 1.0, v13
	v_rcp_f32_e32 v12, v12
	v_rcp_f32_e32 v5, v5
	v_add_f32_e32 v13, 1.0, v16
	v_rcp_f32_e32 v13, v13
	v_and_b32_e32 v19, 0xffff0000, v32
	v_lshlrev_b32_e32 v16, 16, v36
	v_and_b32_e32 v17, 0xffff0000, v36
	v_pk_mul_f32 v[12:13], v[12:13], v[18:19]
	v_exp_f32_e32 v18, v6
	v_pk_fma_f32 v[4:5], v[4:5], v[16:17], v[12:13]
	v_mul_f32_e32 v13, 0xbfb8aa3b, v15
	v_add_f32_e32 v6, 1.0, v14
	v_exp_f32_e32 v13, v13
	v_exp_f32_e32 v14, v7
	v_add_f32_e32 v12, 1.0, v18
	v_rcp_f32_e32 v12, v12
	v_add_f32_e32 v7, 1.0, v13
	v_add_f32_e32 v13, 1.0, v14
	v_rcp_f32_e32 v13, v13
	v_rcp_f32_e32 v6, v6
	v_rcp_f32_e32 v7, v7
	v_lshlrev_b32_e32 v16, 16, v33
	v_and_b32_e32 v17, 0xffff0000, v33
	v_lshlrev_b32_e32 v14, 16, v37
	v_and_b32_e32 v15, 0xffff0000, v37
	v_pk_mul_f32 v[12:13], v[12:13], v[16:17]
	v_mul_f32_e32 v1, 0xbfb8aa3b, v1
	v_exp_f32_e32 v8, v8
	v_exp_f32_e32 v16, v0
	v_pk_fma_f32 v[6:7], v[6:7], v[14:15], v[12:13]
	v_exp_f32_e32 v9, v9
	v_exp_f32_e32 v12, v1
	v_pk_mul_f32 v[2:3], v[2:3], v[54:55] op_sel_hi:[1,0]
	v_add_f32_e32 v0, 1.0, v8
	v_add_f32_e32 v8, 1.0, v16
	v_add_f32_e32 v1, 1.0, v9
	v_add_f32_e32 v9, 1.0, v12
	v_pk_mul_f32 v[10:11], v[10:11], v[54:55] op_sel_hi:[1,0]
	v_rcp_f32_e32 v8, v8
	v_rcp_f32_e32 v9, v9
	v_mul_f32_e32 v2, 0xbfb8aa3b, v2
	v_rcp_f32_e32 v0, v0
	v_rcp_f32_e32 v1, v1
	v_mul_f32_e32 v10, 0xbfb8aa3b, v10
	v_exp_f32_e32 v2, v2
	v_exp_f32_e32 v10, v10
	v_lshlrev_b32_e32 v14, 16, v34
	v_and_b32_e32 v15, 0xffff0000, v34
	v_lshlrev_b32_e32 v12, 16, v38
	v_and_b32_e32 v13, 0xffff0000, v38
	v_pk_mul_f32 v[8:9], v[8:9], v[14:15]
	s_andn2_b64 vcc, exec, s[6:7]
	v_pk_fma_f32 v[8:9], v[0:1], v[12:13], v[8:9]
	v_add_f32_e32 v1, 1.0, v2
	v_mul_f32_e32 v2, 0xbfb8aa3b, v11
	v_add_f32_e32 v0, 1.0, v10
	v_exp_f32_e32 v10, v2
	v_mul_f32_e32 v2, 0xbfb8aa3b, v3
	v_exp_f32_e32 v3, v2
	v_rcp_f32_e32 v2, v1
	v_add_f32_e32 v1, 1.0, v10
	v_rcp_f32_e32 v0, v0
	v_add_f32_e32 v3, 1.0, v3
	v_rcp_f32_e32 v3, v3
	v_rcp_f32_e32 v1, v1
	v_lshlrev_b32_e32 v12, 16, v35
	v_and_b32_e32 v13, 0xffff0000, v35
	v_lshlrev_b32_e32 v10, 16, v39
	v_and_b32_e32 v11, 0xffff0000, v39
	v_pk_mul_f32 v[2:3], v[2:3], v[12:13]
	s_mov_b64 s[6:7], -1
	v_pk_fma_f32 v[10:11], v[0:1], v[10:11], v[2:3]
	v_cvt_pk_bf16_f32 v0, v4, v5
	v_lshl_add_u64 v[4:5], s[50:51], 0, v[40:41]
	v_cvt_pk_bf16_f32 v1, v6, v7
	v_cvt_pk_bf16_f32 v2, v8, v9
	v_cvt_pk_bf16_f32 v3, v10, v11
	v_lshl_add_u64 v[4:5], v[4:5], 0, v[152:153]
	global_store_dwordx4 v[4:5], v[0:3], off
	s_cbranch_vccnz .LBB0_1680
	s_andn2_b64 vcc, exec, s[10:11]
	s_cbranch_vccnz .LBB0_1679
	s_barrier
	s_branch .LBB0_1679
